# norm phase W_in conversion: 8 strided loads per item issued together instead of 8 serialized load+wait blocks
# speedup vs baseline: 1.1058x; 1.0173x over previous
.LBB0_650:
	s_or_b64 exec, exec, s[10:11]
	v_cmp_lt_i32_e32 vcc, -1, v96
	v_lshlrev_b32_e32 v2, 3, v1
	v_lshl_add_u64 v[4:5], v[96:97], 2, s[4:5]
	v_mov_b32_e32 v1, 0
	v_mov_b32_e32 v3, 0
	v_mov_b32_e32 v7, 0
	v_mov_b32_e32 v8, 0
	v_mov_b32_e32 v9, 0
	v_mov_b32_e32 v10, 0
	v_mov_b32_e32 v11, 0
	v_mov_b32_e32 v12, 0
	s_and_saveexec_b64 s[10:11], vcc
	s_cbranch_execz .LBB0_629
	s_mov_b64 s[12:13], 0xc240
	v_mul_u32_u24_e32 v14, 0xc240, v2
	v_mov_b32_e32 v15, 0
	v_lshl_add_u64 v[16:17], v[4:5], 0, v[14:15]
	v_lshl_add_u64 v[18:19], v[16:17], 0, s[12:13]
	v_lshl_add_u64 v[20:21], v[18:19], 0, s[12:13]
	v_lshl_add_u64 v[22:23], v[20:21], 0, s[12:13]
	v_lshl_add_u64 v[24:25], v[22:23], 0, s[12:13]
	v_lshl_add_u64 v[26:27], v[24:25], 0, s[12:13]
	v_lshl_add_u64 v[28:29], v[26:27], 0, s[12:13]
	v_lshl_add_u64 v[30:31], v[28:29], 0, s[12:13]
	global_load_dword v1, v[16:17], off
	global_load_dword v3, v[18:19], off
	global_load_dword v8, v[20:21], off
	global_load_dword v7, v[22:23], off
	global_load_dword v10, v[24:25], off
	global_load_dword v9, v[26:27], off
	global_load_dword v12, v[28:29], off
	global_load_dword v11, v[30:31], off
	s_waitcnt vmcnt(7)
	v_bfe_u32 v14, v1, 16, 1
	v_add3_u32 v1, v1, v14, s33
	v_lshrrev_b32_e32 v1, 16, v1
	s_waitcnt vmcnt(6)
	v_bfe_u32 v15, v3, 16, 1
	v_add3_u32 v3, v3, v15, s33
	v_lshrrev_b32_e32 v3, 16, v3
	s_waitcnt vmcnt(5)
	v_bfe_u32 v14, v8, 16, 1
	v_add3_u32 v8, v8, v14, s33
	v_lshrrev_b32_e32 v8, 16, v8
	s_waitcnt vmcnt(4)
	v_bfe_u32 v15, v7, 16, 1
	v_add3_u32 v7, v7, v15, s33
	v_lshrrev_b32_e32 v7, 16, v7
	s_waitcnt vmcnt(3)
	v_bfe_u32 v14, v10, 16, 1
	v_add3_u32 v10, v10, v14, s33
	v_lshrrev_b32_e32 v10, 16, v10
	s_waitcnt vmcnt(2)
	v_bfe_u32 v15, v9, 16, 1
	v_add3_u32 v9, v9, v15, s33
	v_lshrrev_b32_e32 v9, 16, v9
	s_waitcnt vmcnt(1)
	v_bfe_u32 v14, v12, 16, 1
	v_add3_u32 v12, v12, v14, s33
	v_lshrrev_b32_e32 v12, 16, v12
	s_waitcnt vmcnt(0)
	v_bfe_u32 v15, v11, 16, 1
	v_add3_u32 v11, v11, v15, s33
	v_lshrrev_b32_e32 v11, 16, v11
	s_branch .LBB0_629
